# v27 + grid barrier: each workgroup's cache invalidate issued at arrival (overlaps the wait) instead of after the release
# speedup vs baseline: 1.0053x; 1.0053x over previous
.LBB0_212:
	s_or_b64 exec, exec, s[4:5]
	v_readlane_b32 s4, v253, 50
	v_readlane_b32 s5, v253, 51
	s_waitcnt vmcnt(0)
	s_nop 0
	s_nop 2
	global_atomic_add v64, v216, s[4:5]
	s_waitcnt vmcnt(0)

.LBB0_536:
	v_readlane_b32 s4, v253, 48
	v_readlane_b32 s5, v253, 49
	v_cvt_f32_u32_e32 v1, v2
	v_sub_u32_e32 v4, 0, v2
	v_rcp_iflag_f32_e32 v1, v1
	s_nop 1
	global_atomic_add v3, v64, v216, s[4:5] sc0
	buffer_inv sc1
	v_mul_f32_e32 v1, 0x4f7ffffe, v1
	v_cvt_u32_f32_e32 v1, v1
	v_mul_lo_u32 v4, v4, v1
	v_mul_hi_u32 v4, v1, v4
	v_add_u32_e32 v1, v1, v4
	s_waitcnt vmcnt(1)
	v_mul_hi_u32 v1, v3, v1
	v_mul_lo_u32 v4, v1, v2
	v_sub_u32_e32 v4, v3, v4
	v_add_u32_e32 v5, 1, v1
	v_cmp_ge_u32_e32 vcc, v4, v2
	v_add_u32_e32 v3, 1, v3
	s_nop 0
	v_cndmask_b32_e32 v1, v1, v5, vcc
	v_sub_u32_e32 v5, v4, v2
	v_cndmask_b32_e32 v4, v4, v5, vcc
	v_add_u32_e32 v5, 1, v1
	v_cmp_ge_u32_e32 vcc, v4, v2
	s_nop 1
	v_cndmask_b32_e32 v1, v1, v5, vcc
	v_mul_lo_u32 v4, v2, v1
	v_add_u32_e32 v2, v4, v2
	v_cmp_ne_u32_e32 vcc, v3, v2
	s_and_saveexec_b64 s[4:5], vcc
	s_xor_b64 s[4:5], exec, s[4:5]
	s_cbranch_execz .LBB0_550
	v_readlane_b32 s6, v253, 50
	v_readlane_b32 s7, v253, 51
	s_waitcnt lgkmcnt(0)
	s_nop 3
	global_load_dword v0, v64, s[6:7] sc1
	s_waitcnt vmcnt(0)
	v_cmp_eq_u32_e32 vcc, v0, v1
	s_and_saveexec_b64 s[6:7], vcc
	s_cbranch_execz .LBB0_549
	s_mov_b32 s12, 1
	s_mov_b64 s[8:9], 0
	s_branch .LBB0_540

.LBB0_549:
	s_or_b64 exec, exec, s[6:7]
	s_waitcnt vmcnt(0)
	s_nop 0
	s_waitcnt vmcnt(0)

.LBB0_616:
	v_readlane_b32 s4, v253, 48
	v_readlane_b32 s5, v253, 49
	v_cvt_f32_u32_e32 v1, v2
	v_sub_u32_e32 v4, 0, v2
	v_rcp_iflag_f32_e32 v1, v1
	s_nop 1
	global_atomic_add v3, v64, v216, s[4:5] sc0
	buffer_inv sc1
	v_mul_f32_e32 v1, 0x4f7ffffe, v1
	v_cvt_u32_f32_e32 v1, v1
	v_mul_lo_u32 v4, v4, v1
	v_mul_hi_u32 v4, v1, v4
	v_add_u32_e32 v1, v1, v4
	s_waitcnt vmcnt(1)
	v_mul_hi_u32 v1, v3, v1
	v_mul_lo_u32 v4, v1, v2
	v_sub_u32_e32 v4, v3, v4
	v_add_u32_e32 v5, 1, v1
	v_cmp_ge_u32_e32 vcc, v4, v2
	v_add_u32_e32 v3, 1, v3
	s_nop 0
	v_cndmask_b32_e32 v1, v1, v5, vcc
	v_sub_u32_e32 v5, v4, v2
	v_cndmask_b32_e32 v4, v4, v5, vcc
	v_add_u32_e32 v5, 1, v1
	v_cmp_ge_u32_e32 vcc, v4, v2
	s_nop 1
	v_cndmask_b32_e32 v1, v1, v5, vcc
	v_mul_lo_u32 v4, v2, v1
	v_add_u32_e32 v2, v4, v2
	v_cmp_ne_u32_e32 vcc, v3, v2
	s_and_saveexec_b64 s[4:5], vcc
	s_xor_b64 s[4:5], exec, s[4:5]
	s_cbranch_execz .LBB0_630
	v_readlane_b32 s6, v253, 50
	v_readlane_b32 s7, v253, 51
	s_waitcnt lgkmcnt(0)
	s_nop 3
	global_load_dword v0, v64, s[6:7] sc1
	s_waitcnt vmcnt(0)
	v_cmp_eq_u32_e32 vcc, v0, v1
	s_and_saveexec_b64 s[6:7], vcc
	s_cbranch_execz .LBB0_629
	s_mov_b32 s13, 1
	s_mov_b64 s[8:9], 0
	s_branch .LBB0_620
